# S5 output stage stagger: waves 4-7 delayed by s_sleep 28
# speedup vs baseline: 1.0023x; 1.0023x over previous
; #define LAS __attribute__((address_space(3)))
; #define S5_LAUNDER() int tid_ = tid0, lane_ = lane0; asm volatile("" : "+v"(tid_), "+v"(lane_)); const int tid = tid_, lane = lane_, fr = lane & 15, fq = lane >> 4; (void)tid; (void)fr; (void)fq
; __device__ __forceinline__ void s5_prompt_item_mfma(LAS unsigned char* lds, int tid0, int lane0, int wave, int n, int g, const bf16* USg, const bf16* FTg, const bf16* WTg, const bf16* GTg, ...
;     ...
;     S5_LAUNDER();
; #pragma unroll
;     for (int it = 0; it < 4; ++it) { const int q = tid + 512 * it; *(LAS v4u*)(lds + R2_OFF + q * 16) = ftq[it]; }
;     const f32x4 dk = *(const f32x4*)(dsk + 4 * fq);
;     __syncthreads();
;     bf16x8 hbv[4][4];
; #pragma unroll
;     for (int kk = 0; kk < 4; ++kk)
; #pragma unroll
;         for (int cb = 0; cb < 4; ++cb) hbv[kk][cb] = *(const LAS bf16x8*)(lds + HP_OFF + (16 * cb + fr) * 272 + 64 * kk + 16 * fq);
.LBB0_852:
	s_or_b64 exec, exec, s[54:55]
	v_mov_b32_e32 v201, v196
	v_mov_b32_e32 v2, v192
	s_lshl_b32 s10, s65, 6
	s_barrier
	s_add_u32 s10, s52, s10
	v_ashrrev_i32_e32 v202, 4, v201
	v_lshlrev_b32_e32 v194, 2, v202
	s_addc_u32 s11, s53, 0
	v_ashrrev_i32_e32 v195, 31, v194
	v_lshl_add_u64 v[20:21], v[194:195], 2, s[10:11]
	global_load_dwordx4 v[20:23], v[20:21], off
	s_add_i32 s10, 0, 0x10800
	v_and_b32_e32 v203, 15, v201
	v_lshl_add_u32 v2, v2, 4, s10
	s_waitcnt vmcnt(20)
	ds_write_b128 v2, v[24:27]
	s_waitcnt vmcnt(19)
	ds_write_b128 v2, v[28:31] offset:8192
	s_waitcnt vmcnt(18)
	ds_write_b128 v2, v[32:35] offset:16384
	s_waitcnt vmcnt(17)
	ds_write_b128 v2, v[36:39] offset:24576
	v_and_b32_e32 v2, -16, v201
	s_add_i32 s11, 0, 0x18c00
	v_mul_u32_u24_e32 v24, 0x110, v203
	v_add3_u32 v2, s11, v2, v24
	s_waitcnt lgkmcnt(0)
	s_barrier
	v_readfirstlane_b32 s99, v192
	s_nop 3
	s_lshr_b32 s99, s99, 6
	s_cmp_lt_u32 s99, 4
	s_cbranch_scc1 .Ls5_stag
	s_sleep 28
